# NSA selected branch: off-diagonal blocks use per-token select instead of elementwise mask; s_setprio 1 around MFMA clusters in NSA steps
# speedup vs baseline: 1.0670x; 1.0070x over previous
; DEVI void attn_step(AttnState& st, const bf16x8 (&qf)[2][2], const bfu* Ks, const bfu* Vt, int hi, int lo, int fr, int fq) {
;   const int hi4 = hi - fq * 4, lo4 = lo - fq * 4;
;   f32x4 s[2][4];
;   compute_S(s, qf, Ks, fr, fq);
;   const bool anymask = __builtin_amdgcn_ballot_w64((hi < 63) || (lo >= 0)) != 0ull;
;   if (anymask) {
; #pragma unroll
;     for (int g = 0; g < 2; ++g)
; #pragma unroll
;       for (int ksub = 0; ksub < 4; ++ksub)
; #pragma unroll
;         for (int j = 0; j < 4; ++j) {
;           const int c = ksub * 16 + j;
;           const bool v = (c <= hi4) && (c > lo4);
;           s[g][ksub][j] = v ? s[g][ksub][j] : NEGF;
;         }
;   }
;   float scs[2];
; #pragma unroll
;   for (int g = 0; g < 2; ++g) {
;     float mx = NEGF;
; #pragma unroll
;     for (int ksub = 0; ksub < 4; ++ksub)
; #pragma unroll
;       for (int j = 0; j < 4; ++j) mx = fmaxf(mx, s[g][ksub][j]);
;     mx = fmaxf(mx, __shfl_xor(mx, 16));
;     mx = fmaxf(mx, __shfl_xor(mx, 32));
;     float mn = fmaxf(st.m[g], mx);
;     float sc = __builtin_amdgcn_exp2f(st.m[g] - mn);
; #pragma unroll
;     for (int ksub = 0; ksub < 4; ++ksub)
; #pragma unroll
;       for (int j = 0; j < 4; ++j) s[g][ksub][j] = __builtin_amdgcn_exp2f(s[g][ksub][j] - mn);
;     st.m[g] = mn;
;     scs[g] = sc;
;   }
; DEVI void nsa_item(const Params& p, int l, int item, char* lds_raw, volatile int* nsa_cnt) {
;     ...
;         const bool insel = (mysel >> j) & 1u;
;         const int hi = insel ? ((j == qt) ? tokl : 63) : -1;
;         if (__builtin_amdgcn_ballot_w64(insel) != 0ull) attn_step(st, qf, Kb + kvo, Vb + kvo, hi, -1, fr, fq);
.LBB0_510:
	s_ff1_i32_b32 s4, s4
	v_lshrrev_b32_e32 v110, s4, v157
	v_and_b32_e32 v110, 1, v110
	v_cmp_eq_u32_e64 s[0:1], 1, v110
	v_bfe_u32 v110, v157, s4, 1
	v_cmp_ne_u32_e32 vcc, 0, v110
	s_cbranch_vccz .LBB0_502
	v_lshl_add_u32 v159, s23, 1, v155
	ds_read_b128 v[110:113], v159
	ds_read_b128 v[164:167], v159 offset:64
	s_cmp_eq_u32 s4, s25
	s_cselect_b64 vcc, -1, 0
	s_waitcnt lgkmcnt(1)
	s_setprio 1
	v_mfma_f32_16x16x32_bf16 v[114:117], v[110:113], v[2:5], 0
	v_mfma_f32_16x16x32_bf16 v[118:121], v[110:113], v[10:13], 0
	ds_read_b128 v[110:113], v159 offset:2304
	s_waitcnt lgkmcnt(1)
	v_mfma_f32_16x16x32_bf16 v[118:121], v[164:167], v[14:17], v[118:121]
	s_waitcnt lgkmcnt(0)
	v_mfma_f32_16x16x32_bf16 v[122:125], v[110:113], v[2:5], 0
	v_mfma_f32_16x16x32_bf16 v[126:129], v[110:113], v[10:13], 0
	ds_read_b128 v[110:113], v159 offset:4608
	s_waitcnt lgkmcnt(0)
	v_mfma_f32_16x16x32_bf16 v[130:133], v[110:113], v[2:5], 0
	v_mfma_f32_16x16x32_bf16 v[134:137], v[110:113], v[10:13], 0
	ds_read_b128 v[110:113], v159 offset:6912
	s_waitcnt lgkmcnt(0)
	v_mfma_f32_16x16x32_bf16 v[138:141], v[110:113], v[2:5], 0
	v_mfma_f32_16x16x32_bf16 v[160:163], v[110:113], v[10:13], 0
	v_mfma_f32_16x16x32_bf16 v[110:113], v[164:167], v[6:9], v[114:117]
	ds_read_b128 v[164:167], v159 offset:2368
	s_waitcnt lgkmcnt(0)
	v_mfma_f32_16x16x32_bf16 v[114:117], v[164:167], v[6:9], v[122:125]
	v_mfma_f32_16x16x32_bf16 v[126:129], v[164:167], v[14:17], v[126:129]
	ds_read_b128 v[164:167], v159 offset:4672
	s_waitcnt lgkmcnt(0)
	v_mfma_f32_16x16x32_bf16 v[122:125], v[164:167], v[6:9], v[130:133]
	v_mfma_f32_16x16x32_bf16 v[130:133], v[164:167], v[14:17], v[134:137]
	ds_read_b128 v[164:167], v159 offset:6976
	s_waitcnt lgkmcnt(0)
	v_mfma_f32_16x16x32_bf16 v[134:137], v[164:167], v[6:9], v[138:141]
	s_nop 2
	v_cndmask_b32_e32 v138, 63, v177, vcc
	v_cndmask_b32_e64 v159, -1, v138, s[0:1]
	v_cmp_gt_i32_e32 vcc, 63, v159
	v_mfma_f32_16x16x32_bf16 v[138:141], v[164:167], v[14:17], v[160:163]
	s_setprio 0
	s_mov_b64 s[38:39], -1
	s_cbranch_vccz .LBB0_513
	s_cmp_eq_u32 s4, s25
	s_cbranch_scc1 .Lsel_diag
	s_mov_b64 s[38:39], s[0:1]
	s_branch .LBB0_513
.Lsel_diag:
	v_sub_u32_e32 v159, v159, v203
	v_cmp_lt_i32_e32 vcc, -1, v159
	v_cmp_lt_i32_e64 s[0:1], 0, v159
	v_cmp_lt_i32_e64 s[4:5], 1, v159
	v_cmp_lt_i32_e64 s[38:39], 2, v159
	v_cmp_lt_i32_e64 s[40:41], 15, v159
	v_cmp_lt_i32_e64 s[42:43], 16, v159
	v_cmp_lt_i32_e64 s[44:45], 17, v159
	v_cmp_lt_i32_e64 s[46:47], 18, v159
	v_cmp_lt_i32_e64 s[48:49], 31, v159
	v_cmp_lt_i32_e64 s[50:51], 32, v159
	v_cmp_lt_i32_e64 s[52:53], 33, v159
	v_cmp_lt_i32_e64 s[54:55], 34, v159
	v_cmp_lt_i32_e64 s[56:57], 47, v159
	v_cmp_lt_i32_e64 s[58:59], 48, v159
	v_cmp_lt_i32_e64 s[60:61], 49, v159
	v_cmp_lt_i32_e64 s[62:63], 50, v159
	v_cndmask_b32_e32 v110, v227, v110, vcc
	v_cndmask_b32_e64 v111, v227, v111, s[0:1]
	v_cndmask_b32_e64 v112, v227, v112, s[4:5]
	v_cndmask_b32_e64 v113, v227, v113, s[38:39]
	v_cndmask_b32_e64 v114, v227, v114, s[40:41]
	v_cndmask_b32_e64 v115, v227, v115, s[42:43]
	v_cndmask_b32_e64 v116, v227, v116, s[44:45]
	v_cndmask_b32_e64 v117, v227, v117, s[46:47]
	v_cndmask_b32_e64 v122, v227, v122, s[48:49]
	v_cndmask_b32_e64 v123, v227, v123, s[50:51]
	v_cndmask_b32_e64 v124, v227, v124, s[52:53]
	v_cndmask_b32_e64 v125, v227, v125, s[54:55]
	v_cndmask_b32_e64 v134, v227, v134, s[56:57]
	v_cndmask_b32_e64 v135, v227, v135, s[58:59]
	v_cndmask_b32_e64 v136, v227, v136, s[60:61]
	v_cndmask_b32_e64 v137, v227, v137, s[62:63]
	v_cndmask_b32_e32 v118, v227, v118, vcc
	v_cndmask_b32_e64 v119, v227, v119, s[0:1]
	v_cndmask_b32_e64 v120, v227, v120, s[4:5]
	v_cndmask_b32_e64 v121, v227, v121, s[38:39]
	v_cndmask_b32_e64 v126, v227, v126, s[40:41]
	v_cndmask_b32_e64 v127, v227, v127, s[42:43]
	v_cndmask_b32_e64 v128, v227, v128, s[44:45]
	v_cndmask_b32_e64 v129, v227, v129, s[46:47]
	v_cndmask_b32_e64 v130, v227, v130, s[48:49]
	v_cndmask_b32_e64 v131, v227, v131, s[50:51]
	v_cndmask_b32_e64 v132, v227, v132, s[52:53]
	v_cndmask_b32_e64 v133, v227, v133, s[54:55]
	v_cndmask_b32_e64 v138, v227, v138, s[56:57]
	v_cndmask_b32_e64 v139, v227, v139, s[58:59]
	v_cndmask_b32_e64 v140, v227, v140, s[60:61]
	v_cndmask_b32_e64 v141, v227, v141, s[62:63]
	s_mov_b64 s[38:39], -1
.LBB0_513:
	s_mov_b32 s0, 0xf149f2ca
	v_max3_f32 v159, v110, s0, v111
	v_max3_f32 v159, v159, v112, v113
	v_max3_f32 v159, v159, v114, v115
	v_max3_f32 v159, v159, v116, v117
	v_max3_f32 v159, v159, v122, v123
	v_max3_f32 v159, v159, v124, v125
	v_max3_f32 v159, v159, v134, v135
	v_max3_f32 v159, v159, v136, v137
	v_max3_f32 v160, v118, s0, v119
	v_max3_f32 v160, v160, v120, v121
	v_max3_f32 v160, v160, v126, v127
	v_max3_f32 v160, v160, v128, v129
	v_max3_f32 v160, v160, v130, v131
	v_max3_f32 v160, v160, v132, v133
	v_max3_f32 v160, v160, v138, v139
	v_max3_f32 v160, v160, v140, v141
	v_mov_b32_e32 v161, v159
	v_mov_b32_e32 v246, v160
	s_nop 1
	v_permlane16_swap_b32_e32 v159, v161
	v_permlane16_swap_b32_e32 v160, v246
	v_max_f32_e32 v159, v159, v161
	v_max_f32_e32 v160, v160, v246
	v_mov_b32_e32 v161, v159
	v_mov_b32_e32 v246, v160
	s_nop 1
	v_permlane32_swap_b32_e32 v159, v161
	v_permlane32_swap_b32_e32 v160, v246
	v_max_f32_e32 v159, v159, v161
	v_max_f32_e32 v160, v160, v246
	v_cndmask_b32_e64 v159, v227, v159, s[38:39]
	v_cndmask_b32_e64 v160, v227, v160, s[38:39]
	v_mov_b32_e32 v249, 0x7f800000
	v_max_f32_e32 v159, v152, v159
	v_max_f32_e32 v160, v154, v160
	v_sub_f32_e32 v152, v152, v159
	v_exp_f32_e32 v152, v152
	v_sub_f32_e32 v154, v154, v160
	v_exp_f32_e32 v154, v154
	v_cndmask_b32_e64 v247, v249, v159, s[38:39]
	v_cndmask_b32_e64 v248, v249, v160, s[38:39]
	v_cmp_neq_f32_e32 vcc, 1.0, v152
	s_nop 0
	v_cmp_neq_f32_e64 s[0:1], 1.0, v154
	s_or_b64 vcc, vcc, s[0:1]
	s_cbranch_vccz .LBB0_515
	v_pk_mul_f32 v[104:105], v[104:105], v[152:153] op_sel_hi:[1,0]
	v_pk_mul_f32 v[102:103], v[102:103], v[152:153] op_sel_hi:[1,0]
	v_pk_mul_f32 v[68:69], v[68:69], v[152:153] op_sel_hi:[1,0]
	v_pk_mul_f32 v[66:67], v[66:67], v[152:153] op_sel_hi:[1,0]
	v_pk_mul_f32 v[64:65], v[64:65], v[152:153] op_sel_hi:[1,0]
	v_pk_mul_f32 v[62:63], v[62:63], v[152:153] op_sel_hi:[1,0]
	v_pk_mul_f32 v[60:61], v[60:61], v[152:153] op_sel_hi:[1,0]
	v_pk_mul_f32 v[58:59], v[58:59], v[152:153] op_sel_hi:[1,0]
	v_pk_mul_f32 v[52:53], v[52:53], v[152:153] op_sel_hi:[1,0]
	v_pk_mul_f32 v[50:51], v[50:51], v[152:153] op_sel_hi:[1,0]
	v_pk_mul_f32 v[108:109], v[108:109], v[154:155] op_sel_hi:[1,0]
	v_pk_mul_f32 v[106:107], v[106:107], v[154:155] op_sel_hi:[1,0]
	v_pk_mul_f32 v[80:81], v[80:81], v[154:155] op_sel_hi:[1,0]
	v_pk_mul_f32 v[78:79], v[78:79], v[154:155] op_sel_hi:[1,0]
	v_pk_mul_f32 v[76:77], v[76:77], v[154:155] op_sel_hi:[1,0]
	v_pk_mul_f32 v[74:75], v[74:75], v[154:155] op_sel_hi:[1,0]
	v_pk_mul_f32 v[72:73], v[72:73], v[154:155] op_sel_hi:[1,0]
	v_pk_mul_f32 v[70:71], v[70:71], v[154:155] op_sel_hi:[1,0]
	v_pk_mul_f32 v[56:57], v[56:57], v[154:155] op_sel_hi:[1,0]
	v_pk_mul_f32 v[54:55], v[54:55], v[154:155] op_sel_hi:[1,0]
; template <bool WITH_L>
; DEVI void pv_accum_t(f32x4 (&o)[2][4], f32x4 (&ol)[2], const f32x4 (&pr)[2][4], const bfu* Vt, int fr, int fq) {
; #pragma unroll
;   for (int kp = 0; kp < 2; ++kp) {
;     bf16x8 pf[2];
; #pragma unroll
;     for (int g = 0; g < 2; ++g) {
;       uint4 u;
;       u.x = pack2(pr[g][2 * kp][0], pr[g][2 * kp][1]);
;       u.y = pack2(pr[g][2 * kp][2], pr[g][2 * kp][3]);
;       u.z = pack2(pr[g][2 * kp + 1][0], pr[g][2 * kp + 1][1]);
;       u.w = pack2(pr[g][2 * kp + 1][2], pr[g][2 * kp + 1][3]);
;       pf[g] = *(bf16x8*)&u;
;     }
;     if constexpr (WITH_L) {
;       const short one = (fr == 0) ? (short)0x3F80 : (short)0;
;       const bf16x8 vones = {one, one, one, one, one, one, one, one};
; #pragma unroll
;       for (int g = 0; g < 2; ++g) ol[g] = __builtin_amdgcn_mfma_f32_16x16x32_bf16(vones, pf[g], ol[g], 0, 0, 0);
;     }
; #pragma unroll
;     for (int dsub = 0; dsub < 4; ++dsub) {
;       uint2 lo = *(const uint2*)(Vt + (dsub * 16 + fr) * LS + (2 * kp) * 16 + fq * 4);
;       uint2 hi = *(const uint2*)(Vt + (dsub * 16 + fr) * LS + (2 * kp + 1) * 16 + fq * 4);
;       uint4 u; u.x = lo.x; u.y = lo.y; u.z = hi.x; u.w = hi.y;
;       bf16x8 vf = *(bf16x8*)&u;
; #pragma unroll
;       for (int g = 0; g < 2; ++g) o[g][dsub] = __builtin_amdgcn_mfma_f32_16x16x32_bf16(vf, pf[g], o[g][dsub], 0, 0, 0);
;     }
;   }
; DEVI void attn_step(AttnState& st, const bf16x8 (&qf)[2][2], const bfu* Ks, const bfu* Vt, int hi, int lo, int fr, int fq) {
;     ...
;     float sc = __builtin_amdgcn_exp2f(st.m[g] - mn);
; #pragma unroll
;     for (int ksub = 0; ksub < 4; ++ksub)
; #pragma unroll
;       for (int j = 0; j < 4; ++j) s[g][ksub][j] = __builtin_amdgcn_exp2f(s[g][ksub][j] - mn);
;     st.m[g] = mn;
;     scs[g] = sc;
;   }
;   if (__builtin_amdgcn_ballot_w64((scs[0] != 1.f) || (scs[1] != 1.f)) != 0ull) {
; #pragma unroll
;     for (int g = 0; g < 2; ++g) {
;       st.ol[g] *= scs[g];
; #pragma unroll
;       for (int dsub = 0; dsub < 4; ++dsub) st.o[g][dsub] *= scs[g];
;     }
;   }
;   pv_accum_t<true>(st.o, st.ol, s, Vt, fr, fq);
.LBB0_515:
	v_sub_f32_e32 v126, v126, v248
	v_sub_f32_e32 v127, v127, v248
	v_sub_f32_e32 v116, v116, v247
	v_sub_f32_e32 v117, v117, v247
	v_sub_f32_e32 v110, v110, v247
	v_sub_f32_e32 v111, v111, v247
	v_sub_f32_e32 v112, v112, v247
	v_sub_f32_e32 v113, v113, v247
	v_exp_f32_e32 v126, v126
	v_exp_f32_e32 v127, v127
	v_exp_f32_e32 v116, v116
	v_exp_f32_e32 v117, v117
	v_exp_f32_e32 v110, v110
	v_exp_f32_e32 v111, v111
	v_exp_f32_e32 v112, v112
	v_exp_f32_e32 v113, v113
	v_sub_f32_e32 v118, v118, v248
	v_sub_f32_e32 v119, v119, v248
	v_sub_f32_e32 v120, v120, v248
	v_sub_f32_e32 v121, v121, v248
	v_sub_f32_e32 v114, v114, v247
	v_sub_f32_e32 v115, v115, v247
	v_exp_f32_e32 v118, v118
	v_exp_f32_e32 v119, v119
	v_exp_f32_e32 v120, v120
	v_exp_f32_e32 v121, v121
	v_exp_f32_e32 v114, v114
	v_exp_f32_e32 v115, v115
	v_cvt_pk_bf16_f32 v110, v110, v111
	v_cvt_pk_bf16_f32 v111, v112, v113
	v_cvt_pk_bf16_f32 v113, v116, v117
	v_cvt_pk_bf16_f32 v116, v126, v127
	v_lshl_add_u32 v126, s23, 1, v156
	v_add_u32_e32 v127, 0x4800, v126
	v_cvt_pk_bf16_f32 v112, v114, v115
	v_cvt_pk_bf16_f32 v114, v118, v119
	v_cvt_pk_bf16_f32 v115, v120, v121
	ds_read2_b64 v[118:121], v127 offset1:4
	v_sub_f32_e32 v128, v128, v248
	v_sub_f32_e32 v129, v129, v248
	v_exp_f32_e32 v128, v128
	v_exp_f32_e32 v129, v129
	s_waitcnt lgkmcnt(0)
	s_setprio 1
	v_mfma_f32_16x16x32_bf16 v[66:69], v[118:121], v[110:113], v[66:69]
	v_cvt_pk_bf16_f32 v117, v128, v129
	v_add_u32_e32 v128, 0x5000, v126
	v_add_u32_e32 v129, 0x5800, v126
	v_mfma_f32_16x16x32_bf16 v[78:81], v[118:121], v[114:117], v[78:81]
	ds_read2_b64 v[118:121], v128 offset0:32 offset1:36
	v_add_u32_e32 v126, 0x6000, v126
	v_sub_f32_e32 v138, v138, v248
	s_waitcnt lgkmcnt(0)
	v_mfma_f32_16x16x32_bf16 v[62:65], v[118:121], v[110:113], v[62:65]
	v_sub_f32_e32 v139, v139, v248
	v_sub_f32_e32 v140, v140, v248
	v_sub_f32_e32 v141, v141, v248
	v_mfma_f32_16x16x32_bf16 v[74:77], v[118:121], v[114:117], v[74:77]
	ds_read2_b64 v[118:121], v129 offset0:64 offset1:68
	v_sub_f32_e32 v130, v130, v248
	v_sub_f32_e32 v131, v131, v248
	s_waitcnt lgkmcnt(0)
	v_mfma_f32_16x16x32_bf16 v[58:61], v[118:121], v[110:113], v[58:61]
	v_sub_f32_e32 v132, v132, v248
	v_sub_f32_e32 v133, v133, v248
	v_sub_f32_e32 v134, v134, v247
	v_mfma_f32_16x16x32_bf16 v[70:73], v[118:121], v[114:117], v[70:73]
	ds_read2_b64 v[118:121], v126 offset0:96 offset1:100
	v_sub_f32_e32 v135, v135, v247
	v_sub_f32_e32 v136, v136, v247
	s_waitcnt lgkmcnt(0)
	v_mfma_f32_16x16x32_bf16 v[50:53], v[118:121], v[110:113], v[50:53]
	v_sub_f32_e32 v137, v137, v247
	v_sub_f32_e32 v122, v122, v247
	v_sub_f32_e32 v123, v123, v247
	v_mfma_f32_16x16x32_bf16 v[54:57], v[118:121], v[114:117], v[54:57]
	ds_read2_b64 v[118:121], v127 offset0:8 offset1:12
	v_sub_f32_e32 v124, v124, v247
	v_sub_f32_e32 v125, v125, v247
	v_exp_f32_e32 v138, v138
	v_exp_f32_e32 v139, v139
	v_exp_f32_e32 v140, v140
	v_exp_f32_e32 v141, v141
	v_exp_f32_e32 v130, v130
	v_exp_f32_e32 v131, v131
	v_exp_f32_e32 v132, v132
	v_exp_f32_e32 v133, v133
	v_exp_f32_e32 v134, v134
	v_exp_f32_e32 v135, v135
	v_exp_f32_e32 v136, v136
	v_exp_f32_e32 v137, v137
	v_exp_f32_e32 v122, v122
	v_exp_f32_e32 v123, v123
	v_exp_f32_e32 v124, v124
	v_exp_f32_e32 v125, v125
	v_mfma_f32_16x16x32_bf16 v[102:105], v[82:85], v[110:113], v[102:105]
	v_cvt_pk_bf16_f32 v110, v122, v123
	v_cvt_pk_bf16_f32 v112, v134, v135
	v_cvt_pk_bf16_f32 v111, v124, v125
	v_mfma_f32_16x16x32_bf16 v[106:109], v[82:85], v[114:117], v[106:109]
	v_cvt_pk_bf16_f32 v113, v136, v137
	v_cvt_pk_bf16_f32 v114, v130, v131
	v_cvt_pk_bf16_f32 v115, v132, v133
	v_cvt_pk_bf16_f32 v116, v138, v139
	v_cvt_pk_bf16_f32 v117, v140, v141
	s_waitcnt lgkmcnt(0)
	v_mfma_f32_16x16x32_bf16 v[66:69], v[118:121], v[110:113], v[66:69]
	v_mfma_f32_16x16x32_bf16 v[78:81], v[118:121], v[114:117], v[78:81]
	ds_read2_b64 v[118:121], v128 offset0:40 offset1:44
	s_waitcnt lgkmcnt(0)
	v_mfma_f32_16x16x32_bf16 v[62:65], v[118:121], v[110:113], v[62:65]
	v_mfma_f32_16x16x32_bf16 v[74:77], v[118:121], v[114:117], v[74:77]
	ds_read2_b64 v[118:121], v129 offset0:72 offset1:76
	s_waitcnt lgkmcnt(0)
	v_mfma_f32_16x16x32_bf16 v[58:61], v[118:121], v[110:113], v[58:61]
	v_mfma_f32_16x16x32_bf16 v[70:73], v[118:121], v[114:117], v[70:73]
	ds_read2_b64 v[118:121], v126 offset0:104 offset1:108
	v_mfma_f32_16x16x32_bf16 v[102:105], v[82:85], v[110:113], v[102:105]
	v_mfma_f32_16x16x32_bf16 v[106:109], v[82:85], v[114:117], v[106:109]
	s_waitcnt lgkmcnt(0)
	v_mfma_f32_16x16x32_bf16 v[50:53], v[118:121], v[110:113], v[50:53]
	v_mfma_f32_16x16x32_bf16 v[54:57], v[118:121], v[114:117], v[54:57]
	s_setprio 0
	s_branch .LBB0_503

; DEVI void compute_S(f32x4 (&s)[2][4], const bf16x8 (&qf)[2][2], const bfu* Ks, int fr, int fq) {
; #pragma unroll
;   for (int g = 0; g < 2; ++g)
; #pragma unroll
;     for (int k = 0; k < 4; ++k) s[g][k] = f32x4{0.f, 0.f, 0.f, 0.f};
; #pragma unroll
;   for (int ks = 0; ks < 2; ++ks)
; #pragma unroll
;     for (int ksub = 0; ksub < 4; ++ksub) {
;       bf16x8 kf = *(const bf16x8*)(Ks + (ksub * 16 + fr) * LS + ks * 32 + fq * 8);
; #pragma unroll
;       for (int g = 0; g < 2; ++g) s[g][ksub] = __builtin_amdgcn_mfma_f32_16x16x32_bf16(kf, qf[g][ks], s[g][ksub], 0, 0, 0);
;     }
; }
; DEVI void attn_step(AttnState& st, const bf16x8 (&qf)[2][2], const bfu* Ks, const bfu* Vt, int hi, int lo, int fr, int fq) {
;   const int hi4 = hi - fq * 4, lo4 = lo - fq * 4;
;   f32x4 s[2][4];
;   compute_S(s, qf, Ks, fr, fq);
;   const bool anymask = __builtin_amdgcn_ballot_w64((hi < 63) || (lo >= 0)) != 0ull;
;   if (anymask) {
; #pragma unroll
;     for (int g = 0; g < 2; ++g)
; #pragma unroll
;       for (int ksub = 0; ksub < 4; ++ksub)
; #pragma unroll
;         for (int j = 0; j < 4; ++j) {
;           const int c = ksub * 16 + j;
;           const bool v = (c <= hi4) && (c > lo4);
;           s[g][ksub][j] = v ? s[g][ksub][j] : NEGF;
;         }
;   }
.LBB0_521:
	v_add3_u32 v214, v187, v183, v199
	ds_read_b128 v[142:145], v214
	ds_read_b128 v[210:213], v214 offset:64
	s_cmp_eq_u32 s25, s28
	s_cselect_b64 vcc, -1, 0
	s_cmp_eq_u32 s23, s28
	v_cndmask_b32_e32 v204, 63, v177, vcc
	s_cselect_b64 vcc, -1, 0
	v_cndmask_b32_e32 v205, -1, v177, vcc
	v_cmp_gt_i32_e32 vcc, 63, v204
	s_waitcnt lgkmcnt(1)
	s_setprio 1
	v_mfma_f32_16x16x32_bf16 v[146:149], v[142:145], v[2:5], 0
	v_cmp_lt_i32_e64 s[0:1], -1, v205
	s_or_b64 vcc, vcc, s[0:1]
	v_mfma_f32_16x16x32_bf16 v[150:153], v[142:145], v[10:13], 0
	ds_read_b128 v[142:145], v214 offset:2304
	s_waitcnt lgkmcnt(1)
	v_mfma_f32_16x16x32_bf16 v[150:153], v[210:213], v[14:17], v[150:153]
	s_waitcnt lgkmcnt(0)
	v_mfma_f32_16x16x32_bf16 v[154:157], v[142:145], v[2:5], 0
	v_mfma_f32_16x16x32_bf16 v[158:161], v[142:145], v[10:13], 0
	ds_read_b128 v[142:145], v214 offset:4608
	s_waitcnt lgkmcnt(0)
	v_mfma_f32_16x16x32_bf16 v[162:165], v[142:145], v[2:5], 0
	v_mfma_f32_16x16x32_bf16 v[166:169], v[142:145], v[10:13], 0
	ds_read_b128 v[142:145], v214 offset:6912
	s_waitcnt lgkmcnt(0)
	v_mfma_f32_16x16x32_bf16 v[170:173], v[142:145], v[2:5], 0
	v_mfma_f32_16x16x32_bf16 v[206:209], v[142:145], v[10:13], 0
	v_mfma_f32_16x16x32_bf16 v[142:145], v[210:213], v[6:9], v[146:149]
	ds_read_b128 v[210:213], v214 offset:2368
	s_waitcnt lgkmcnt(0)
	v_mfma_f32_16x16x32_bf16 v[146:149], v[210:213], v[6:9], v[154:157]
	v_mfma_f32_16x16x32_bf16 v[158:161], v[210:213], v[14:17], v[158:161]
	ds_read_b128 v[210:213], v214 offset:4672
	s_waitcnt lgkmcnt(0)
	v_mfma_f32_16x16x32_bf16 v[154:157], v[210:213], v[6:9], v[162:165]
	v_mfma_f32_16x16x32_bf16 v[162:165], v[210:213], v[14:17], v[166:169]
	ds_read_b128 v[210:213], v214 offset:6976
	s_waitcnt lgkmcnt(0)
	v_mfma_f32_16x16x32_bf16 v[166:169], v[210:213], v[6:9], v[170:173]
	v_mfma_f32_16x16x32_bf16 v[170:173], v[210:213], v[14:17], v[206:209]
	s_setprio 0
	s_cbranch_vccz .LBB0_523
	v_sub_u32_e32 v205, v205, v203
	v_sub_u32_e32 v204, v204, v203
	v_cmp_lt_i32_e64 s[4:5], -1, v204
	v_cmp_gt_i32_e64 s[38:39], 0, v205
	s_and_b64 s[4:5], s[4:5], s[38:39]
	v_cmp_lt_i32_e64 s[38:39], 0, v204
	v_cmp_gt_i32_e64 s[40:41], 1, v205
	s_and_b64 s[38:39], s[38:39], s[40:41]
	v_cmp_lt_i32_e64 s[40:41], 1, v204
	v_cmp_gt_i32_e64 s[42:43], 2, v205
	s_and_b64 s[40:41], s[40:41], s[42:43]
	v_cmp_lt_i32_e64 s[42:43], 2, v204
	v_cmp_gt_i32_e64 s[44:45], 3, v205
	s_and_b64 s[42:43], s[42:43], s[44:45]
	v_cmp_lt_i32_e64 s[44:45], 15, v204
	v_cmp_gt_i32_e64 s[46:47], 16, v205
	s_and_b64 s[44:45], s[44:45], s[46:47]
	v_cmp_lt_i32_e64 s[46:47], 16, v204
	v_cmp_gt_i32_e64 s[48:49], 17, v205
	s_and_b64 s[46:47], s[46:47], s[48:49]
	v_cmp_lt_i32_e64 s[48:49], 17, v204
	v_cmp_gt_i32_e64 s[50:51], 18, v205
	s_and_b64 s[48:49], s[48:49], s[50:51]
	v_cmp_lt_i32_e64 s[50:51], 18, v204
	v_cmp_gt_i32_e64 s[52:53], 19, v205
	s_and_b64 s[50:51], s[50:51], s[52:53]
	v_cmp_lt_i32_e64 s[52:53], 31, v204
	v_cmp_gt_i32_e64 s[54:55], 32, v205
	s_and_b64 s[52:53], s[52:53], s[54:55]
	v_cmp_lt_i32_e64 s[54:55], 32, v204
	v_cmp_gt_i32_e64 s[56:57], 33, v205
	s_and_b64 s[54:55], s[54:55], s[56:57]
	v_cmp_lt_i32_e64 s[56:57], 33, v204
	v_cmp_gt_i32_e64 s[58:59], 34, v205
	v_cmp_lt_i32_e32 vcc, 47, v204
	v_cmp_gt_i32_e64 s[0:1], 48, v205
	s_and_b64 s[56:57], s[56:57], s[58:59]
	v_cmp_lt_i32_e64 s[58:59], 34, v204
	v_cmp_gt_i32_e64 s[60:61], 35, v205
	s_and_b64 s[58:59], s[58:59], s[60:61]
	s_and_b64 vcc, vcc, s[0:1]
	v_cmp_lt_i32_e64 s[0:1], 48, v204
	v_cmp_gt_i32_e64 s[60:61], 49, v205
	s_and_b64 s[0:1], s[0:1], s[60:61]
	v_cmp_lt_i32_e64 s[60:61], 49, v204
	v_cmp_gt_i32_e64 s[62:63], 50, v205
	s_and_b64 s[60:61], s[60:61], s[62:63]
	v_cmp_lt_i32_e64 s[62:63], 50, v204
	v_cmp_gt_i32_e64 s[64:65], 51, v205
	s_and_b64 s[62:63], s[62:63], s[64:65]
	v_cndmask_b32_e64 v142, v227, v142, s[4:5]
	v_cndmask_b32_e64 v143, v227, v143, s[38:39]
	v_cndmask_b32_e64 v144, v227, v144, s[40:41]
	v_cndmask_b32_e64 v145, v227, v145, s[42:43]
	v_cndmask_b32_e64 v146, v227, v146, s[44:45]
	v_cndmask_b32_e64 v147, v227, v147, s[46:47]
	v_cndmask_b32_e64 v148, v227, v148, s[48:49]
	v_cndmask_b32_e64 v149, v227, v149, s[50:51]
	v_cndmask_b32_e64 v154, v227, v154, s[52:53]
	v_cndmask_b32_e64 v155, v227, v155, s[54:55]
	v_cndmask_b32_e64 v156, v227, v156, s[56:57]
	v_cndmask_b32_e64 v157, v227, v157, s[58:59]
	v_cndmask_b32_e32 v166, v227, v166, vcc
	v_cndmask_b32_e64 v167, v227, v167, s[0:1]
	v_cndmask_b32_e64 v168, v227, v168, s[60:61]
	v_cndmask_b32_e64 v169, v227, v169, s[62:63]
	v_cndmask_b32_e64 v150, v227, v150, s[4:5]
	v_cndmask_b32_e64 v151, v227, v151, s[38:39]
	v_cndmask_b32_e64 v152, v227, v152, s[40:41]
	v_cndmask_b32_e64 v153, v227, v153, s[42:43]
	v_cndmask_b32_e64 v158, v227, v158, s[44:45]
	v_cndmask_b32_e64 v159, v227, v159, s[46:47]
	v_cndmask_b32_e64 v160, v227, v160, s[48:49]
	v_cndmask_b32_e64 v161, v227, v161, s[50:51]
	v_cndmask_b32_e64 v162, v227, v162, s[52:53]
	v_cndmask_b32_e64 v163, v227, v163, s[54:55]
	v_cndmask_b32_e64 v164, v227, v164, s[56:57]
	v_cndmask_b32_e64 v165, v227, v165, s[58:59]
	v_cndmask_b32_e32 v170, v227, v170, vcc
	v_cndmask_b32_e64 v171, v227, v171, s[0:1]
	v_cndmask_b32_e64 v172, v227, v172, s[60:61]
	v_cndmask_b32_e64 v173, v227, v173, s[62:63]

; template <bool WITH_L>
; DEVI void pv_accum_t(f32x4 (&o)[2][4], f32x4 (&ol)[2], const f32x4 (&pr)[2][4], const bfu* Vt, int fr, int fq) {
; #pragma unroll
;   for (int kp = 0; kp < 2; ++kp) {
;     bf16x8 pf[2];
; #pragma unroll
;     for (int g = 0; g < 2; ++g) {
;       uint4 u;
;       u.x = pack2(pr[g][2 * kp][0], pr[g][2 * kp][1]);
;       u.y = pack2(pr[g][2 * kp][2], pr[g][2 * kp][3]);
;       u.z = pack2(pr[g][2 * kp + 1][0], pr[g][2 * kp + 1][1]);
;       u.w = pack2(pr[g][2 * kp + 1][2], pr[g][2 * kp + 1][3]);
;       pf[g] = *(bf16x8*)&u;
;     }
;     if constexpr (WITH_L) {
;       const short one = (fr == 0) ? (short)0x3F80 : (short)0;
;       const bf16x8 vones = {one, one, one, one, one, one, one, one};
; #pragma unroll
;       for (int g = 0; g < 2; ++g) ol[g] = __builtin_amdgcn_mfma_f32_16x16x32_bf16(vones, pf[g], ol[g], 0, 0, 0);
;     }
; #pragma unroll
;     for (int dsub = 0; dsub < 4; ++dsub) {
;       uint2 lo = *(const uint2*)(Vt + (dsub * 16 + fr) * LS + (2 * kp) * 16 + fq * 4);
;       uint2 hi = *(const uint2*)(Vt + (dsub * 16 + fr) * LS + (2 * kp + 1) * 16 + fq * 4);
;       uint4 u; u.x = lo.x; u.y = lo.y; u.z = hi.x; u.w = hi.y;
;       bf16x8 vf = *(bf16x8*)&u;
; #pragma unroll
;       for (int g = 0; g < 2; ++g) o[g][dsub] = __builtin_amdgcn_mfma_f32_16x16x32_bf16(vf, pf[g], o[g][dsub], 0, 0, 0);
;     }
;   }
; DEVI void attn_step(AttnState& st, const bf16x8 (&qf)[2][2], const bfu* Ks, const bfu* Vt, int hi, int lo, int fr, int fq) {
;     ...
;     float sc = __builtin_amdgcn_exp2f(st.m[g] - mn);
; #pragma unroll
;     for (int ksub = 0; ksub < 4; ++ksub)
; #pragma unroll
;       for (int j = 0; j < 4; ++j) s[g][ksub][j] = __builtin_amdgcn_exp2f(s[g][ksub][j] - mn);
;     st.m[g] = mn;
;     scs[g] = sc;
;   }
;   if (__builtin_amdgcn_ballot_w64((scs[0] != 1.f) || (scs[1] != 1.f)) != 0ull) {
; #pragma unroll
;     for (int g = 0; g < 2; ++g) {
;       st.ol[g] *= scs[g];
; #pragma unroll
;       for (int dsub = 0; dsub < 4; ++dsub) st.o[g][dsub] *= scs[g];
;     }
;   }
;   pv_accum_t<true>(st.o, st.ol, s, Vt, fr, fq);
.LBB0_525:
	v_sub_f32_e32 v150, v150, v205
	v_sub_f32_e32 v151, v151, v205
	v_sub_f32_e32 v146, v146, v204
	v_sub_f32_e32 v147, v147, v204
	v_sub_f32_e32 v142, v142, v204
	v_sub_f32_e32 v143, v143, v204
	v_sub_f32_e32 v144, v144, v204
	v_sub_f32_e32 v145, v145, v204
	v_sub_f32_e32 v158, v158, v205
	v_sub_f32_e32 v159, v159, v205
	v_exp_f32_e32 v150, v150
	v_exp_f32_e32 v151, v151
	v_exp_f32_e32 v146, v146
	v_exp_f32_e32 v147, v147
	v_sub_f32_e32 v148, v148, v204
	v_sub_f32_e32 v149, v149, v204
	v_exp_f32_e32 v142, v142
	v_exp_f32_e32 v143, v143
	v_exp_f32_e32 v144, v144
	v_exp_f32_e32 v145, v145
	v_exp_f32_e32 v158, v158
	v_exp_f32_e32 v159, v159
	v_exp_f32_e32 v148, v148
	v_exp_f32_e32 v149, v149
	v_sub_f32_e32 v152, v152, v205
	v_sub_f32_e32 v153, v153, v205
	v_exp_f32_e32 v152, v152
	v_exp_f32_e32 v153, v153
	v_cvt_pk_bf16_f32 v142, v142, v143
	v_cvt_pk_bf16_f32 v143, v144, v145
	v_cvt_pk_bf16_f32 v144, v146, v147
	v_cvt_pk_bf16_f32 v146, v150, v151
	v_lshlrev_b32_e32 v150, 1, v203
	v_cvt_pk_bf16_f32 v145, v148, v149
	v_cvt_pk_bf16_f32 v148, v158, v159
	v_add3_u32 v158, v187, v199, v150
	v_add_u32_e32 v159, 0x4800, v158
	v_cvt_pk_bf16_f32 v147, v152, v153
	ds_read2_b64 v[150:153], v159 offset1:4
	v_sub_f32_e32 v160, v160, v205
	v_sub_f32_e32 v161, v161, v205
	v_exp_f32_e32 v160, v160
	v_exp_f32_e32 v161, v161
	s_waitcnt lgkmcnt(0)
	s_setprio 1
	v_mfma_f32_16x16x32_bf16 v[110:113], v[150:153], v[142:145], v[110:113]
	v_cvt_pk_bf16_f32 v149, v160, v161
	v_add_u32_e32 v160, 0x5000, v158
	v_add_u32_e32 v161, 0x5800, v158
	v_mfma_f32_16x16x32_bf16 v[106:109], v[150:153], v[146:149], v[106:109]
	ds_read2_b64 v[150:153], v160 offset0:32 offset1:36
	v_add_u32_e32 v158, 0x6000, v158
	v_sub_f32_e32 v170, v170, v205
	s_waitcnt lgkmcnt(0)
	v_mfma_f32_16x16x32_bf16 v[102:105], v[150:153], v[142:145], v[102:105]
	v_sub_f32_e32 v171, v171, v205
	v_sub_f32_e32 v172, v172, v205
	v_sub_f32_e32 v173, v173, v205
	v_mfma_f32_16x16x32_bf16 v[98:101], v[150:153], v[146:149], v[98:101]
	ds_read2_b64 v[150:153], v161 offset0:64 offset1:68
	v_sub_f32_e32 v162, v162, v205
	v_sub_f32_e32 v163, v163, v205
	s_waitcnt lgkmcnt(0)
	v_mfma_f32_16x16x32_bf16 v[94:97], v[150:153], v[142:145], v[94:97]
	v_sub_f32_e32 v164, v164, v205
	v_sub_f32_e32 v165, v165, v205
	v_sub_f32_e32 v166, v166, v204
	v_mfma_f32_16x16x32_bf16 v[90:93], v[150:153], v[146:149], v[90:93]
	ds_read2_b64 v[150:153], v158 offset0:96 offset1:100
	v_sub_f32_e32 v167, v167, v204
	v_sub_f32_e32 v168, v168, v204
	s_waitcnt lgkmcnt(0)
	v_mfma_f32_16x16x32_bf16 v[86:89], v[150:153], v[142:145], v[86:89]
	v_sub_f32_e32 v169, v169, v204
	v_sub_f32_e32 v154, v154, v204
	v_sub_f32_e32 v155, v155, v204
	v_mfma_f32_16x16x32_bf16 v[82:85], v[150:153], v[146:149], v[82:85]
	ds_read2_b64 v[150:153], v159 offset0:8 offset1:12
	v_sub_f32_e32 v156, v156, v204
	v_sub_f32_e32 v157, v157, v204
	v_exp_f32_e32 v170, v170
	v_exp_f32_e32 v171, v171
	v_exp_f32_e32 v172, v172
	v_exp_f32_e32 v173, v173
	v_exp_f32_e32 v162, v162
	v_exp_f32_e32 v163, v163
	v_exp_f32_e32 v164, v164
	v_exp_f32_e32 v165, v165
	v_exp_f32_e32 v166, v166
	v_exp_f32_e32 v167, v167
	v_exp_f32_e32 v168, v168
	v_exp_f32_e32 v169, v169
	v_exp_f32_e32 v154, v154
	v_exp_f32_e32 v155, v155
	v_exp_f32_e32 v156, v156
	v_exp_f32_e32 v157, v157
	v_mfma_f32_16x16x32_bf16 v[138:141], v[114:117], v[142:145], v[138:141]
	v_cvt_pk_bf16_f32 v142, v154, v155
	v_cvt_pk_bf16_f32 v144, v166, v167
	v_cvt_pk_bf16_f32 v143, v156, v157
	v_mfma_f32_16x16x32_bf16 v[134:137], v[114:117], v[146:149], v[134:137]
	v_cvt_pk_bf16_f32 v145, v168, v169
	v_cvt_pk_bf16_f32 v146, v162, v163
	v_cvt_pk_bf16_f32 v147, v164, v165
	v_cvt_pk_bf16_f32 v148, v170, v171
	v_cvt_pk_bf16_f32 v149, v172, v173
	s_waitcnt lgkmcnt(0)
	v_mfma_f32_16x16x32_bf16 v[110:113], v[150:153], v[142:145], v[110:113]
	v_xor_b32_e32 v179, 0x1200, v179
	s_add_i32 s28, s28, 1
	s_add_i32 s30, s30, 64
	v_mfma_f32_16x16x32_bf16 v[106:109], v[150:153], v[146:149], v[106:109]
	ds_read2_b64 v[150:153], v160 offset0:40 offset1:44
	s_andn2_b64 vcc, exec, s[36:37]
	s_waitcnt lgkmcnt(0)
	v_mfma_f32_16x16x32_bf16 v[102:105], v[150:153], v[142:145], v[102:105]
	v_mfma_f32_16x16x32_bf16 v[98:101], v[150:153], v[146:149], v[98:101]
	ds_read2_b64 v[150:153], v161 offset0:72 offset1:76
	s_waitcnt lgkmcnt(0)
	v_mfma_f32_16x16x32_bf16 v[94:97], v[150:153], v[142:145], v[94:97]
	v_mfma_f32_16x16x32_bf16 v[90:93], v[150:153], v[146:149], v[90:93]
	ds_read2_b64 v[150:153], v158 offset0:104 offset1:108
	v_mfma_f32_16x16x32_bf16 v[138:141], v[114:117], v[142:145], v[138:141]
	v_mfma_f32_16x16x32_bf16 v[134:137], v[114:117], v[146:149], v[134:137]
	s_waitcnt lgkmcnt(0)
	v_mfma_f32_16x16x32_bf16 v[86:89], v[150:153], v[142:145], v[86:89]
	v_mfma_f32_16x16x32_bf16 v[82:85], v[150:153], v[146:149], v[82:85]
	s_cbranch_vccz .LBB0_479
	v_mov_b32_e32 v198, v204
	v_mov_b32_e32 v200, v205
	s_setprio 0
	s_branch .LBB0_519
